# scan staging: DMA issue ordered by first consumer (w_k, q_dec slots of both sets first)
# baseline (speedup 1.0000x reference)
.LBB0_159:
	s_and_b64 vcc, exec, s[4:5]
	s_cbranch_vccz .Lscan_nostage
	s_setprio 3
	s_xor_b32 s6, s11, 1
	s_mul_i32 s6, s6, 0x12000
	s_add_i32 s6, s6, s8
	s_mov_b32 s7, m0
	s_add_i32 s12, s6, 0xfffff000
	s_add_i32 m0, s6, 0x0
	s_nop 0
	global_load_lds_dwordx4 v[62:63], off
	s_add_i32 m0, s12, 0x0
	s_nop 0
	global_load_lds_dwordx4 v[80:81], off
	s_add_i32 m0, s6, 0x2000
	s_nop 0
	global_load_lds_dwordx4 v[64:65], off
	s_add_i32 m0, s12, 0x2000
	s_nop 0
	global_load_lds_dwordx4 v[82:83], off
	s_add_i32 m0, s6, 0x4000
	s_nop 0
	global_load_lds_dwordx4 v[66:67], off
	s_add_i32 m0, s12, 0x4000
	s_nop 0
	global_load_lds_dwordx4 v[86:87], off
	s_add_i32 m0, s6, 0x6000
	s_nop 0
	global_load_lds_dwordx4 v[68:69], off
	s_add_i32 m0, s12, 0x6000
	s_nop 0
	global_load_lds_dwordx4 v[88:89], off
	s_add_i32 m0, s6, 0x8000
	s_nop 0
	global_load_lds_dwordx4 v[70:71], off
	s_add_i32 m0, s12, 0x8000
	s_nop 0
	global_load_lds_dwordx4 v[90:91], off
	s_add_i32 m0, s6, 0xa000
	s_nop 0
	global_load_lds_dwordx4 v[72:73], off
	s_add_i32 m0, s12, 0xa000
	s_nop 0
	global_load_lds_dwordx4 v[92:93], off
	s_add_i32 m0, s6, 0xc000
	s_nop 0
	global_load_lds_dwordx4 v[74:75], off
	s_add_i32 m0, s12, 0xc000
	s_nop 0
	global_load_lds_dwordx4 v[94:95], off
	s_add_i32 m0, s6, 0xe000
	s_nop 0
	global_load_lds_dwordx4 v[76:77], off
	s_add_i32 m0, s12, 0xe000
	s_nop 0
	global_load_lds_dwordx4 v[96:97], off
	s_add_i32 m0, s6, 0x10000
	s_nop 0
	global_load_lds_dwordx4 v[78:79], off
	s_add_i32 m0, s12, 0x10000
	s_nop 0
	global_load_lds_dwordx4 v[98:99], off
	s_mov_b32 m0, s7
	s_setprio 0
	s_mov_b64 s[12:13], 0x4000
	s_mov_b64 s[14:15], 0x8000
	v_lshl_add_u64 v[62:63], v[62:63], 0, s[12:13]
	v_lshl_add_u64 v[64:65], v[64:65], 0, s[12:13]
	v_lshl_add_u64 v[66:67], v[66:67], 0, s[12:13]
	v_lshl_add_u64 v[68:69], v[68:69], 0, s[12:13]
	v_lshl_add_u64 v[70:71], v[70:71], 0, s[12:13]
	v_lshl_add_u64 v[72:73], v[72:73], 0, s[12:13]
	v_lshl_add_u64 v[74:75], v[74:75], 0, s[34:35]
	v_lshl_add_u64 v[76:77], v[76:77], 0, s[14:15]
	v_lshl_add_u64 v[78:79], v[78:79], 0, s[14:15]
	v_lshl_add_u64 v[80:81], v[80:81], 0, s[12:13]
	v_lshl_add_u64 v[82:83], v[82:83], 0, s[12:13]
	v_lshl_add_u64 v[86:87], v[86:87], 0, s[12:13]
	v_lshl_add_u64 v[88:89], v[88:89], 0, s[12:13]
	v_lshl_add_u64 v[90:91], v[90:91], 0, s[12:13]
	v_lshl_add_u64 v[92:93], v[92:93], 0, s[12:13]
	v_lshl_add_u64 v[94:95], v[94:95], 0, s[34:35]
	v_lshl_add_u64 v[96:97], v[96:97], 0, s[14:15]
	v_lshl_add_u64 v[98:99], v[98:99], 0, s[14:15]
